# same wave stagger with a longer step (w*40*64 cycles)
# baseline (speedup 1.0000x reference)
; #define OPAQUE_IDS int tx = threadIdx.x; int bx = blockIdx.x; asm volatile("" : "+v"(tx), "+s"(bx));
; DI void norm_phase(const Params& p, int layer, int which, bool lat_only, const float* __restrict__ part, int npart, int srcmode) {
;     OPAQUE_IDS
;     const int lane = tx & 63, gw = bx * 8 + (tx >> 6);
.Lstg_2:
	s_cmp_eq_u32 s98, 0
	s_cbranch_scc1 .Lstg_2_done
	s_sleep 40
	s_sub_u32 s98, s98, 1
	s_branch .Lstg_2
